# attention unit prologue de-serialised: RoPE table loads issued up front with counted waits, first-tile K fragment reads all in flight before the QK MFMAs (on top of trimmed GEMM barrier hand-off)
# speedup vs baseline: 1.0301x; 1.0301x over previous
; __device__ __forceinline__ unsigned cvtpk(float lo, float hi) { unsigned r; asm volatile("v_cvt_pk_bf16_f32 %0, %1, %2" : "=v"(r) : "v"(lo), "v"(hi)); return r; }
; #define SWRITE(off, i) do { *(bf16x8*)((char*)V_lds + (off) + vst) = sr_[i].v; *(bf16x8*)((char*)K_lds + (off) + kst) = sr_[i].k; \
;     if (has_r) *(bf16x8*)((char*)K_lds + (off) + rst) = sr_[i].r; } while (0)
; __device__ __forceinline__ unsigned cvtpk(float lo, float hi) { unsigned r; asm volatile("v_cvt_pk_bf16_f32 %0, %1, %2" : "=v"(r) : "v"(lo), "v"(hi)); return r; }
; __device__ __forceinline__ void attn_unit(const bf16_t* __restrict__ Qb, const bf16_t* __restrict__ KNh, const bf16_t* __restrict__ KRb, const bf16_t* __restrict__ Vh, ...
;     ...
;   const bf16_t* Qw = Qb + (long)(wid * QBLK + r32) * LDQ + hi * 8;
; #pragma unroll
;   for (int d0 = 0; d0 < 6; ++d0) qr[d0] = *reinterpret_cast<const bf16x8*>(Qw + d0 * 16);
;   {
;     const int pos = row_pos(qrow0 + wid * QBLK + r32); const float* cp = ropec + pos * 16 + 8 * hi; const float* sp = ropes + pos * 16 + 8 * hi;
;     unsigned w1[4], w2[4];
; #pragma unroll
;     for (int e = 0; e < 8; e += 2) { float o1[2], o2[2];
; #pragma unroll
;       for (int f = 0; f < 2; ++f) { const float x1 = __uint_as_float(((unsigned)(unsigned short)qr[4][e + f]) << 16), x2 = __uint_as_float(((unsigned)(unsigned short)qr[5][e + f]) << 16); const float c = cp[e + f], s = sp[e + f];
;         o1[f] = x1 * c - x2 * s; o2[f] = x1 * s + x2 * c; }
;       w1[e >> 1] = cvtpk(o1[0], o1[1]); w2[e >> 1] = cvtpk(o2[0], o2[1]); }
;     u32x4 v1 = {w1[0], w1[1], w1[2], w1[3]}, v2 = {w2[0], w2[1], w2[2], w2[3]}; qr[4] = *reinterpret_cast<bf16x8*>(&v1); qr[5] = *reinterpret_cast<bf16x8*>(&v2); }
;     ...
;   f32x16 pA0, pA1, pB0, pB1; float alA, alB; bf16x8 pa0, pa1, pa2, pa3;
;   int o_prev = 2 * BUF, o_cur = 0, o_next = BUF;
;   asm volatile("s_waitcnt vmcnt(0)" ::: "memory"); SWRITE(0, SE); __syncthreads();
.LBB0_713:
	s_lshl_b32 s10, s10, 8
	s_add_i32 s30, s10, s8
	s_mul_i32 s10, s30, 0x600
	s_mul_hi_i32 s8, s30, 0x600
	s_add_u32 s31, s52, s10
	s_mul_i32 s10, s36, 0x60
	s_addc_u32 s8, s53, s8
	s_lshl_b64 s[28:29], s[10:11], 1
	s_add_u32 s58, s31, s28
	s_addc_u32 s59, s8, s29
	v_and_b32_e32 v189, 31, v96
	s_lshl_b32 s28, s9, 5
	v_or_b32_e32 v46, s28, v189
	v_mov_b64_e32 v[44:45], s[58:59]
	v_mad_i64_i32 v[44:45], s[8:9], v46, s49, v[44:45]
	s_add_i32 s8, s28, s30
	v_bfe_u32 v190, v96, 5, 1
	v_add_u32_e32 v70, s8, v189
	v_and_b32_e32 v59, 48, v176
	v_lshlrev_b32_e32 v176, 4, v190
	v_cmp_gt_i32_e32 vcc, s47, v70
	v_lshl_add_u64 v[68:69], v[44:45], 0, v[176:177]
	global_load_dwordx4 v[44:47], v[68:69], off offset:128
	global_load_dwordx4 v[64:67], v[68:69], off offset:160
	v_cndmask_b32_e32 v71, v185, v188, vcc
	v_and_b32_e32 v70, v71, v70
	v_lshlrev_b32_e32 v70, 6, v70
	v_mov_b32_e32 v71, v177
	v_lshl_add_u64 v[72:73], s[16:17], 0, v[70:71]
	v_and_b32_e32 v74, 32, v96
	v_mov_b32_e32 v75, v177
	v_lshl_add_u64 v[72:73], v[72:73], 0, v[74:75]
	v_lshl_add_u64 v[70:71], s[18:19], 0, v[70:71]
	v_lshl_add_u64 v[70:71], v[70:71], 0, v[74:75]
	global_load_dwordx2 v[74:75], v[72:73], off
	global_load_dwordx2 v[76:77], v[70:71], off
	global_load_dwordx2 v[204:205], v[70:71], off offset:8
	global_load_dwordx2 v[206:207], v[72:73], off offset:8
	global_load_dwordx2 v[208:209], v[70:71], off offset:16
	global_load_dwordx2 v[210:211], v[72:73], off offset:16
	global_load_dwordx2 v[212:213], v[70:71], off offset:24
	global_load_dwordx2 v[214:215], v[72:73], off offset:24
	global_load_dwordx4 v[156:159], v[68:69], off
	global_load_dwordx4 v[152:155], v[68:69], off offset:32
	global_load_dwordx4 v[148:151], v[68:69], off offset:64
	global_load_dwordx4 v[136:139], v[68:69], off offset:96
	v_lshrrev_b32_e32 v41, 5, v41
	v_lshlrev_b32_e32 v43, 8, v43
	v_lshl_or_b32 v42, v42, 4, v184
	s_and_b64 vcc, exec, s[6:7]
	s_waitcnt vmcnt(13)
	v_lshlrev_b32_e32 v68, 16, v44
	s_waitcnt vmcnt(12)
	v_lshlrev_b32_e32 v69, 16, v64
	v_and_b32_e32 v79, 0xffff0000, v64
	v_and_b32_e32 v78, 0xffff0000, v44
	s_waitcnt vmcnt(11)
	v_mov_b32_e32 v82, v74
	s_waitcnt vmcnt(10)
	v_mov_b32_e32 v83, v76
	v_mov_b32_e32 v84, v76
	v_mov_b32_e32 v85, v74
	v_mov_b32_e32 v76, v75
	v_mov_b32_e32 v74, v77
	v_pk_mul_f32 v[82:83], v[82:83], v[68:69]
	v_pk_mul_f32 v[68:69], v[84:85], v[68:69]
	v_pk_mul_f32 v[76:77], v[76:77], v[78:79]
	v_pk_mul_f32 v[74:75], v[74:75], v[78:79]
	v_add_f32_e32 v64, v68, v69
	v_sub_f32_e32 v68, v76, v77
	v_add_f32_e32 v69, v74, v75
	v_sub_f32_e32 v44, v82, v83
	v_cvt_pk_bf16_f32 v140, v44, v68
	v_cvt_pk_bf16_f32 v128, v64, v69
	v_lshlrev_b32_e32 v77, 16, v45
	v_lshlrev_b32_e32 v76, 16, v65
	v_and_b32_e32 v45, 0xffff0000, v45
	v_and_b32_e32 v44, 0xffff0000, v65
	s_waitcnt vmcnt(9)
	v_mov_b32_e32 v64, v204
	s_waitcnt vmcnt(8)
	v_mov_b32_e32 v65, v206
	v_mov_b32_e32 v78, v206
	v_mov_b32_e32 v79, v204
	v_mov_b32_e32 v74, v205
	v_mov_b32_e32 v68, v207
	v_mov_b32_e32 v75, v207
	v_mov_b32_e32 v69, v205
	v_pk_mul_f32 v[64:65], v[64:65], v[76:77]
	v_pk_mul_f32 v[76:77], v[78:79], v[76:77]
	v_pk_mul_f32 v[74:75], v[74:75], v[44:45]
	v_pk_mul_f32 v[44:45], v[68:69], v[44:45]
	v_sub_f32_e32 v64, v65, v64
	v_add_f32_e32 v65, v76, v77
	v_add_f32_e32 v44, v44, v45
	v_sub_f32_e32 v68, v75, v74
	v_cvt_pk_bf16_f32 v141, v64, v68
	v_cvt_pk_bf16_f32 v129, v65, v44
	v_and_b32_e32 v75, 0xffff0000, v46
	v_and_b32_e32 v74, 0xffff0000, v66
	v_lshlrev_b32_e32 v69, 16, v46
	v_lshlrev_b32_e32 v68, 16, v66
	s_waitcnt vmcnt(7)
	v_mov_b32_e32 v76, v208
	s_waitcnt vmcnt(6)
	v_mov_b32_e32 v77, v210
	v_mov_b32_e32 v78, v210
	v_mov_b32_e32 v79, v208
	v_mov_b32_e32 v64, v209
	v_mov_b32_e32 v44, v211
	v_mov_b32_e32 v65, v211
	v_mov_b32_e32 v45, v209
	v_pk_mul_f32 v[64:65], v[64:65], v[74:75]
	v_pk_mul_f32 v[44:45], v[44:45], v[74:75]
	v_pk_mul_f32 v[76:77], v[76:77], v[68:69]
	v_pk_mul_f32 v[68:69], v[78:79], v[68:69]
	v_sub_f32_e32 v64, v65, v64
	v_add_f32_e32 v44, v44, v45
	v_sub_f32_e32 v46, v77, v76
	v_add_f32_e32 v66, v68, v69
	v_cvt_pk_bf16_f32 v142, v46, v64
	v_cvt_pk_bf16_f32 v130, v66, v44
	v_xor_b32_e32 v68, v40, v96
	v_and_b32_e32 v69, 0xfffff0, v40
	v_lshlrev_b32_e32 v70, 1, v40
	v_lshlrev_b32_e32 v66, 8, v40
	v_lshrrev_b32_e32 v71, 1, v40
	v_and_b32_e32 v40, 3, v40
	v_lshlrev_b32_e32 v68, 4, v68
	v_and_or_b32 v69, v70, 8, v69
	v_lshrrev_b32_e32 v46, 2, v96
	v_and_or_b32 v40, v71, 4, v40
	v_and_or_b32 v194, v68, s70, v66
	v_lshrrev_b32_e32 v254, 4, v66
	v_and_b32_e32 v254, 0x80, v254
	v_or_b32_e32 v194, v194, v254
	v_lshrrev_b32_e32 v66, 1, v69
	v_lshlrev_b32_e32 v46, 4, v46
	v_lshl_or_b32 v40, v40, 6, v59
	v_or_b32_e32 v41, v66, v41
	v_and_b32_e32 v46, 0xf0, v46
	v_lshl_or_b32 v40, v41, 9, v40
	v_bitop3_b32 v195, v42, v43, v46 bitop3:0xde
	v_add_u32_e32 v196, 0, v40
	v_lshlrev_b32_e32 v41, 16, v47
	v_lshlrev_b32_e32 v40, 16, v67
	v_and_b32_e32 v43, 0xffff0000, v47
	v_and_b32_e32 v42, 0xffff0000, v67
	v_add_u32_e32 v82, 0, v194
	v_add_u32_e32 v59, 0, v195
	s_waitcnt vmcnt(5)
	v_mov_b32_e32 v46, v212
	s_waitcnt vmcnt(4)
	v_mov_b32_e32 v47, v214
	v_mov_b32_e32 v66, v214
	v_mov_b32_e32 v67, v212
	v_mov_b32_e32 v64, v213
	v_mov_b32_e32 v44, v215
	v_mov_b32_e32 v65, v215
	v_mov_b32_e32 v45, v213
	v_pk_mul_f32 v[46:47], v[46:47], v[40:41]
	v_pk_mul_f32 v[40:41], v[66:67], v[40:41]
	v_pk_mul_f32 v[64:65], v[64:65], v[42:43]
	v_pk_mul_f32 v[42:43], v[44:45], v[42:43]
	v_sub_f32_e32 v44, v47, v46
	v_add_f32_e32 v40, v40, v41
	v_sub_f32_e32 v41, v65, v64
	v_add_f32_e32 v42, v42, v43
	v_cvt_pk_bf16_f32 v143, v44, v41
	v_cvt_pk_bf16_f32 v131, v40, v42
	s_waitcnt vmcnt(0)
	ds_write_b128 v196, v[36:39]
	ds_write_b128 v82, v[32:35] offset:49152
	s_cbranch_vccnz .LBB0_715
	ds_write_b128 v59, v[132:135] offset:49152
; template <bool FIRST> __device__ __forceinline__ void partialSM(f32x16& p0, f32x16& p1, float& m_ref, f32x16& negm, float& alpha) {
;   constexpr float THR2 = THR * 1.4426950408889634f;
;   float pmax = p0[0];
; #pragma unroll
;   for (int r = 1; r < 16; ++r) pmax = fmaxf(pmax, p0[r]);
; #pragma unroll
;   for (int r = 0; r < 16; ++r) pmax = fmaxf(pmax, p1[r]);
;   { auto rr = __builtin_amdgcn_permlane32_swap(__float_as_uint(pmax), __float_as_uint(pmax), false, false);
;     pmax = fmaxf(__uint_as_float(rr[0]), __uint_as_float(rr[1])); }
;   alpha = 1.f;
;   if (FIRST || !__builtin_expect(__all(pmax <= THR2), 1)) {
;     const float dl = FIRST ? pmax : fmaxf(pmax, 0.f);
;     m_ref += dl; alpha = FIRST ? 1.f : __builtin_amdgcn_exp2f(-dl);
; #pragma unroll
;     for (int r = 0; r < 16; ++r) { p0[r] -= dl; p1[r] -= dl; }
; #pragma unroll
;     for (int r = 0; r < 16; ++r) negm[r] = -m_ref;
;     asm volatile("" : "+v"(negm));
;   }
; __device__ __forceinline__ void qkt(f32x16& p0, f32x16& p1, const bf16_t* Ks, const bf16x8* qr, const f32x16& negm, int r32, int hi) {
; #pragma unroll
;   for (int d0 = 0; d0 < 6; ++d0) { int cb = (d0 * 16 + hi * 8) * 2;
;     bf16x8 b0 = *reinterpret_cast<const bf16x8*>((const char*)Ks + KSWZ(r32, cb));
;     bf16x8 b1 = *reinterpret_cast<const bf16x8*>((const char*)Ks + KSWZ(32 + r32, cb));
;     if (d0 == 0) { p0 = __builtin_amdgcn_mfma_f32_32x32x16_bf16(b0, qr[0], negm, 0, 0, 0); p1 = __builtin_amdgcn_mfma_f32_32x32x16_bf16(b1, qr[0], negm, 0, 0, 0); }
;     else { p0 = __builtin_amdgcn_mfma_f32_32x32x16_bf16(b0, qr[d0], p0, 0, 0, 0); p1 = __builtin_amdgcn_mfma_f32_32x32x16_bf16(b1, qr[d0], p1, 0, 0, 0); } }
; }
.LBB0_715:
	v_lshlrev_b32_e32 v32, 4, v189
	v_lshlrev_b32_e32 v68, 8, v189
	v_and_b32_e32 v69, 0xf0, v32
	v_bitop3_b32 v197, v176, v68, v69 bitop3:0xde
	v_or_b32_e32 v70, 32, v176
	v_bitop3_b32 v198, v70, v68, v69 bitop3:0xde
	v_or_b32_e32 v70, 64, v176
	v_bitop3_b32 v199, v70, v68, v69 bitop3:0xde
	v_or_b32_e32 v70, 0x60, v176
	v_bitop3_b32 v200, v70, v68, v69 bitop3:0xde
	v_or_b32_e32 v70, 0x80, v176
	v_bitop3_b32 v201, v70, v68, v69 bitop3:0xde
	v_or_b32_e32 v71, 0xa0, v176
	v_bitop3_b32 v202, v71, v68, v69 bitop3:0xde
	s_waitcnt lgkmcnt(0)
	s_barrier
	ds_read_b128 v[204:207], v197 offset:49152
	ds_read_b128 v[208:211], v197 offset:57344
	ds_read_b128 v[212:215], v198 offset:49152
	ds_read_b128 v[216:219], v198 offset:57344
	ds_read_b128 v[220:223], v199 offset:49152
	ds_read_b128 v[224:227], v199 offset:57344
	ds_read_b128 v[228:231], v200 offset:49152
	ds_read_b128 v[232:235], v200 offset:57344
	ds_read_b128 v[236:239], v201 offset:49152
	ds_read_b128 v[240:243], v201 offset:57344
	ds_read_b128 v[244:247], v202 offset:49152
	ds_read_b128 v[248:251], v202 offset:57344
	v_add_co_u32_e32 v62, vcc, 0x20000, v62
	s_waitcnt lgkmcnt(11)
	v_mfma_f32_32x32x16_bf16 v[32:47], v[204:207], v[156:159], v[16:31]
	v_addc_co_u32_e32 v63, vcc, 0, v63, vcc
	v_add_co_u32_e32 v60, vcc, 0x20000, v60
	s_waitcnt lgkmcnt(10)
	v_mfma_f32_32x32x16_bf16 v[16:31], v[208:211], v[156:159], v[16:31]
	v_addc_co_u32_e32 v61, vcc, 0, v61, vcc
	s_and_b64 vcc, exec, s[6:7]
	s_waitcnt lgkmcnt(9)
	v_mfma_f32_32x32x16_bf16 v[32:47], v[212:215], v[152:155], v[32:47]
	s_waitcnt lgkmcnt(8)
	v_mfma_f32_32x32x16_bf16 v[16:31], v[216:219], v[152:155], v[16:31]
	s_waitcnt lgkmcnt(7)
	v_mfma_f32_32x32x16_bf16 v[32:47], v[220:223], v[148:151], v[32:47]
	s_waitcnt lgkmcnt(6)
	v_mfma_f32_32x32x16_bf16 v[16:31], v[224:227], v[148:151], v[16:31]
	s_waitcnt lgkmcnt(5)
	v_mfma_f32_32x32x16_bf16 v[32:47], v[228:231], v[136:139], v[32:47]
	s_waitcnt lgkmcnt(4)
	v_mfma_f32_32x32x16_bf16 v[16:31], v[232:235], v[136:139], v[16:31]
	s_waitcnt lgkmcnt(3)
	v_mfma_f32_32x32x16_bf16 v[32:47], v[236:239], v[140:143], v[32:47]
	s_waitcnt lgkmcnt(1)
	v_mfma_f32_32x32x16_bf16 v[32:47], v[244:247], v[128:131], v[32:47]
	v_mfma_f32_32x32x16_bf16 v[16:31], v[240:243], v[140:143], v[16:31]
	s_nop 10
	v_max_f32_e32 v72, v33, v33
	v_max_f32_e32 v73, v32, v32
	v_max_f32_e32 v72, v73, v72
	v_max3_f32 v64, v72, v34, v35
	v_max3_f32 v64, v64, v36, v37
	v_max3_f32 v64, v64, v38, v39
	v_max3_f32 v64, v64, v40, v41
	s_waitcnt lgkmcnt(0)
	v_mfma_f32_32x32x16_bf16 v[16:31], v[248:251], v[128:131], v[16:31]
	v_max3_f32 v64, v64, v42, v43
	v_max3_f32 v64, v64, v44, v45
	v_max3_f32 v64, v64, v46, v47
	s_nop 8
	v_max3_f32 v64, v64, v16, v17
	v_max3_f32 v64, v64, v18, v19
	v_max3_f32 v64, v64, v20, v21
	v_max3_f32 v64, v64, v22, v23
	v_max3_f32 v64, v64, v24, v25
	v_max3_f32 v64, v64, v26, v27
	v_max3_f32 v64, v64, v28, v29
	v_max3_f32 v64, v64, v30, v31
	v_mov_b32_e32 v65, v64
	s_nop 1
	v_permlane32_swap_b32_e32 v64, v65
	v_max_f32_e32 v65, v65, v65
	v_max_f32_e32 v64, v64, v64
	v_max_f32_e32 v97, v64, v65
	v_add_f32_e32 v191, 0, v97
	v_xor_b32_e32 v64, 0x80000000, v191
	v_mov_b32_e32 v65, v64
	v_mov_b32_e32 v66, v64
	v_mov_b32_e32 v67, v64
	v_mov_b32_e32 v68, v64
	v_mov_b32_e32 v69, v64
	v_mov_b32_e32 v70, v64
	v_mov_b32_e32 v71, v64
	v_mov_b32_e32 v72, v64
	v_mov_b32_e32 v73, v64
	v_mov_b32_e32 v74, v64
	v_mov_b32_e32 v75, v64
	v_mov_b32_e32 v76, v64
	v_mov_b32_e32 v77, v64
	v_mov_b32_e32 v78, v64
	v_mov_b32_e32 v79, v64
	global_load_dwordx4 v[160:163], v[62:63], off
	global_load_dwordx4 v[164:167], v[60:61], off
	s_cbranch_vccnz .LBB0_753
	v_add_co_u32_e32 v60, vcc, 0x2000, v80
	s_nop 1
	v_addc_co_u32_e32 v61, vcc, 0, v81, vcc
	global_load_dwordx4 v[132:135], v[60:61], off
	s_mov_b64 s[8:9], -1
	s_and_b64 vcc, exec, s[34:35]
	s_cbranch_vccnz .LBB0_754
